# P2x scan loop state update rewritten by hand: all LDS reads of a kt block issued together (one LDS round trip per block instead of 3-5), next block's reads behind the block's last MFMA
# speedup vs baseline: 1.0080x; 1.0080x over previous
.LBB0_576:
	v_cndmask_b32_e64 v16, 0, v32, s[24:25]
	v_cndmask_b32_e64 v17, 0, v33, s[30:31]
	v_cndmask_b32_e64 v18, 0, v34, s[34:35]
	v_cndmask_b32_e64 v19, 0, v35, s[36:37]
	v_cvt_pk_bf16_f32 v28, v16, v17
	v_cvt_pk_bf16_f32 v29, v18, v19
	v_cndmask_b32_e64 v20, 0, v36, s[22:23]
	v_cndmask_b32_e64 v21, v37, 0, s[24:25]
	v_cndmask_b32_e64 v22, 0, v38, s[26:27]
	v_cndmask_b32_e64 v23, 0, v39, s[28:29]
	v_cvt_pk_bf16_f32 v16, v24, v25
	v_cvt_pk_bf16_f32 v17, v26, v27
	v_add_u32_e32 v143, 0, v182
	v_add_u32_e32 v144, v164, v165
	v_mfma_f32_16x16x16_bf16 v[16:19], v[28:29], v[16:17], v[24:27]
	s_and_b64 vcc, exec, s[40:41]
	s_nop 1
	v_cvt_pk_bf16_f32 v24, v20, v21
	v_cvt_pk_bf16_f32 v25, v22, v23
	s_nop 1
	v_mfma_f32_16x16x16_bf16 v[20:23], v[28:29], v[24:25], 0
	v_mfma_f32_16x16x16_bf16 v[24:27], v[24:25], v[28:29], 0
	s_nop 7
	v_cvt_pk_bf16_f32 v24, v24, v25
	v_cvt_pk_bf16_f32 v25, v26, v27
	v_cvt_pk_bf16_f32 v26, v16, v17
	v_cvt_pk_bf16_f32 v27, v18, v19
	s_nop 1
	v_mfma_f32_16x16x16_bf16 v[16:19], v[24:25], v[26:27], v[16:19]
	v_cvt_pk_bf16_f32 v26, v20, v21
	v_cvt_pk_bf16_f32 v27, v22, v23
	s_nop 1
	v_mfma_f32_16x16x16_bf16 v[20:23], v[24:25], v[26:27], 0
	v_mfma_f32_16x16x16_bf16 v[24:27], v[26:27], v[24:25], 0
	s_nop 6
	v_cvt_pk_bf16_f32 v20, v20, v21
	v_cvt_pk_bf16_f32 v21, v22, v23
	v_cvt_pk_bf16_f32 v24, v24, v25
	v_cvt_pk_bf16_f32 v25, v26, v27
	v_cvt_pk_bf16_f32 v26, v16, v17
	v_cvt_pk_bf16_f32 v27, v18, v19
	v_mfma_f32_16x16x16_bf16 v[20:23], v[20:21], v[24:25], 0
	s_nop 0
	v_mfma_f32_16x16x16_bf16 v[16:19], v[24:25], v[26:27], v[16:19]
	s_nop 5
	v_cvt_pk_bf16_f32 v20, v20, v21
	v_cvt_pk_bf16_f32 v21, v22, v23
	v_cvt_pk_bf16_f32 v22, v16, v17
	v_cvt_pk_bf16_f32 v23, v18, v19
	s_nop 1
	v_mfma_f32_16x16x16_bf16 v[16:19], v[20:21], v[22:23], v[16:19]
	ds_read_b128 v[20:23], v143 offset:13568
	ds_read_b32 v206, v144 offset:13568
	ds_read_u16 v252, v49 offset:4608
	ds_read_u16 v253, v49 offset:4752
	ds_read_u16 v254, v49 offset:4896
	ds_read_u16 v255, v49 offset:5040
	s_and_b64 vcc, exec, s[40:41]
	s_cbranch_vccnz .Lkt0_nov
	s_nop 1
	v_cvt_pk_bf16_f32 v16, v16, v17
	v_cvt_pk_bf16_f32 v17, v18, v19
	ds_read_u16 v18, v49 offset:6912
	ds_read_u16 v19, v49 offset:7056
	ds_read_u16 v205, v49 offset:7200
	ds_read_u16 v251, v49 offset:7344
	s_waitcnt lgkmcnt(0)
	v_pk_mul_f32 v[12:13], v[12:13], v[20:21]
	v_pk_mul_f32 v[14:15], v[14:15], v[22:23]
	v_lshlrev_b32_e32 v252, 16, v252
	v_lshlrev_b32_e32 v253, 16, v253
	v_lshlrev_b32_e32 v254, 16, v254
	v_lshlrev_b32_e32 v255, 16, v255
	v_pk_mul_f32 v[252:253], v[206:207], v[252:253] op_sel_hi:[0,1]
	v_pk_mul_f32 v[254:255], v[206:207], v[254:255] op_sel_hi:[0,1]
	v_cvt_pk_bf16_f32 v252, v252, v253
	v_cvt_pk_bf16_f32 v253, v254, v255
	v_lshlrev_b32_e32 v18, 16, v18
	v_lshlrev_b32_e32 v19, 16, v19
	v_mfma_f32_16x16x16_bf16 v[12:15], v[252:253], v[16:17], v[12:15]
	v_lshlrev_b32_e32 v205, 16, v205
	v_lshlrev_b32_e32 v251, 16, v251
	v_pk_mul_f32 v[18:19], v[206:207], v[18:19] op_sel_hi:[0,1]
	v_mul_f32_e32 v205, v206, v205
	v_mul_f32_e32 v251, v206, v251
	v_cvt_pk_bf16_f32 v18, v18, v19
	v_cvt_pk_bf16_f32 v19, v205, v251
	s_nop 1
	v_mfma_f32_16x16x16_bf16 v[12:15], v[18:19], v[98:99], v[12:15]
	ds_read_b128 v[20:23], v143 offset:13632
	ds_read_b32 v206, v144 offset:13632
	ds_read_u16 v252, v49 offset:4640
	ds_read_u16 v253, v49 offset:4784
	ds_read_u16 v254, v49 offset:4928
	ds_read_u16 v255, v49 offset:5072
	ds_read_u16 v18, v49 offset:6944
	ds_read_u16 v19, v49 offset:7088
	ds_read_u16 v205, v49 offset:7232
	ds_read_u16 v251, v49 offset:7376
	s_waitcnt lgkmcnt(0)
	v_pk_mul_f32 v[8:9], v[8:9], v[20:21]
	v_pk_mul_f32 v[10:11], v[10:11], v[22:23]
	v_lshlrev_b32_e32 v252, 16, v252
	v_lshlrev_b32_e32 v253, 16, v253
	v_lshlrev_b32_e32 v254, 16, v254
	v_lshlrev_b32_e32 v255, 16, v255
	v_pk_mul_f32 v[252:253], v[206:207], v[252:253] op_sel_hi:[0,1]
	v_pk_mul_f32 v[254:255], v[206:207], v[254:255] op_sel_hi:[0,1]
	v_cvt_pk_bf16_f32 v252, v252, v253
	v_cvt_pk_bf16_f32 v253, v254, v255
	v_lshlrev_b32_e32 v18, 16, v18
	v_lshlrev_b32_e32 v19, 16, v19
	v_mfma_f32_16x16x16_bf16 v[8:11], v[252:253], v[16:17], v[8:11]
	v_lshlrev_b32_e32 v205, 16, v205
	v_lshlrev_b32_e32 v251, 16, v251
	v_pk_mul_f32 v[18:19], v[206:207], v[18:19] op_sel_hi:[0,1]
	v_mul_f32_e32 v205, v206, v205
	v_mul_f32_e32 v251, v206, v251
	v_cvt_pk_bf16_f32 v18, v18, v19
	v_cvt_pk_bf16_f32 v19, v205, v251
	s_nop 1
	v_mfma_f32_16x16x16_bf16 v[8:11], v[18:19], v[98:99], v[8:11]
	ds_read_b128 v[20:23], v143 offset:13696
	ds_read_b32 v206, v144 offset:13696
	ds_read_u16 v252, v49 offset:4672
	ds_read_u16 v253, v49 offset:4816
	ds_read_u16 v254, v49 offset:4960
	ds_read_u16 v255, v49 offset:5104
	ds_read_u16 v18, v49 offset:6976
	ds_read_u16 v19, v49 offset:7120
	ds_read_u16 v205, v49 offset:7264
	ds_read_u16 v251, v49 offset:7408
	s_waitcnt lgkmcnt(0)
	v_pk_mul_f32 v[4:5], v[4:5], v[20:21]
	v_pk_mul_f32 v[6:7], v[6:7], v[22:23]
	v_lshlrev_b32_e32 v252, 16, v252
	v_lshlrev_b32_e32 v253, 16, v253
	v_lshlrev_b32_e32 v254, 16, v254
	v_lshlrev_b32_e32 v255, 16, v255
	v_pk_mul_f32 v[252:253], v[206:207], v[252:253] op_sel_hi:[0,1]
	v_pk_mul_f32 v[254:255], v[206:207], v[254:255] op_sel_hi:[0,1]
	v_cvt_pk_bf16_f32 v252, v252, v253
	v_cvt_pk_bf16_f32 v253, v254, v255
	v_lshlrev_b32_e32 v18, 16, v18
	v_lshlrev_b32_e32 v19, 16, v19
	v_mfma_f32_16x16x16_bf16 v[4:7], v[252:253], v[16:17], v[4:7]
	v_lshlrev_b32_e32 v205, 16, v205
	v_lshlrev_b32_e32 v251, 16, v251
	v_pk_mul_f32 v[18:19], v[206:207], v[18:19] op_sel_hi:[0,1]
	v_mul_f32_e32 v205, v206, v205
	v_mul_f32_e32 v251, v206, v251
	v_cvt_pk_bf16_f32 v18, v18, v19
	v_cvt_pk_bf16_f32 v19, v205, v251
	s_nop 1
	v_mfma_f32_16x16x16_bf16 v[4:7], v[18:19], v[98:99], v[4:7]
	ds_read_b128 v[20:23], v143 offset:13760
	ds_read_b32 v206, v144 offset:13760
	ds_read_u16 v252, v49 offset:4704
	ds_read_u16 v253, v49 offset:4848
	ds_read_u16 v254, v49 offset:4992
	ds_read_u16 v255, v49 offset:5136
	ds_read_u16 v18, v49 offset:7008
	ds_read_u16 v19, v49 offset:7152
	ds_read_u16 v205, v49 offset:7296
	ds_read_u16 v251, v49 offset:7440
	s_waitcnt lgkmcnt(0)
	v_pk_mul_f32 v[0:1], v[0:1], v[20:21]
	v_pk_mul_f32 v[2:3], v[2:3], v[22:23]
	v_lshlrev_b32_e32 v252, 16, v252
	v_lshlrev_b32_e32 v253, 16, v253
	v_lshlrev_b32_e32 v254, 16, v254
	v_lshlrev_b32_e32 v255, 16, v255
	v_pk_mul_f32 v[252:253], v[206:207], v[252:253] op_sel_hi:[0,1]
	v_pk_mul_f32 v[254:255], v[206:207], v[254:255] op_sel_hi:[0,1]
	v_cvt_pk_bf16_f32 v252, v252, v253
	v_cvt_pk_bf16_f32 v253, v254, v255
	v_lshlrev_b32_e32 v18, 16, v18
	v_lshlrev_b32_e32 v19, 16, v19
	v_mfma_f32_16x16x16_bf16 v[0:3], v[252:253], v[16:17], v[0:3]
	v_lshlrev_b32_e32 v205, 16, v205
	v_lshlrev_b32_e32 v251, 16, v251
	v_pk_mul_f32 v[18:19], v[206:207], v[18:19] op_sel_hi:[0,1]
	v_mul_f32_e32 v205, v206, v205
	v_mul_f32_e32 v251, v206, v251
	v_cvt_pk_bf16_f32 v18, v18, v19
	v_cvt_pk_bf16_f32 v19, v205, v251
	s_nop 1
	v_mfma_f32_16x16x16_bf16 v[0:3], v[18:19], v[98:99], v[0:3]
	s_branch .Lkt0_end
.Lkt0_nov:
	s_nop 3
	s_nop 1
	v_cvt_pk_bf16_f32 v16, v16, v17
	v_cvt_pk_bf16_f32 v17, v18, v19
	s_waitcnt lgkmcnt(0)
	v_pk_mul_f32 v[12:13], v[12:13], v[20:21]
	v_pk_mul_f32 v[14:15], v[14:15], v[22:23]
	v_lshlrev_b32_e32 v252, 16, v252
	v_lshlrev_b32_e32 v253, 16, v253
	v_lshlrev_b32_e32 v254, 16, v254
	v_lshlrev_b32_e32 v255, 16, v255
	v_pk_mul_f32 v[252:253], v[206:207], v[252:253] op_sel_hi:[0,1]
	v_pk_mul_f32 v[254:255], v[206:207], v[254:255] op_sel_hi:[0,1]
	v_cvt_pk_bf16_f32 v252, v252, v253
	v_cvt_pk_bf16_f32 v253, v254, v255
	s_nop 1
	v_mfma_f32_16x16x16_bf16 v[12:15], v[252:253], v[16:17], v[12:15]
	ds_read_b128 v[20:23], v143 offset:13632
	ds_read_b32 v206, v144 offset:13632
	ds_read_u16 v252, v49 offset:4640
	ds_read_u16 v253, v49 offset:4784
	ds_read_u16 v254, v49 offset:4928
	ds_read_u16 v255, v49 offset:5072
	s_waitcnt lgkmcnt(0)
	v_pk_mul_f32 v[8:9], v[8:9], v[20:21]
	v_pk_mul_f32 v[10:11], v[10:11], v[22:23]
	v_lshlrev_b32_e32 v252, 16, v252
	v_lshlrev_b32_e32 v253, 16, v253
	v_lshlrev_b32_e32 v254, 16, v254
	v_lshlrev_b32_e32 v255, 16, v255
	v_pk_mul_f32 v[252:253], v[206:207], v[252:253] op_sel_hi:[0,1]
	v_pk_mul_f32 v[254:255], v[206:207], v[254:255] op_sel_hi:[0,1]
	v_cvt_pk_bf16_f32 v252, v252, v253
	v_cvt_pk_bf16_f32 v253, v254, v255
	s_nop 1
	v_mfma_f32_16x16x16_bf16 v[8:11], v[252:253], v[16:17], v[8:11]
	ds_read_b128 v[20:23], v143 offset:13696
	ds_read_b32 v206, v144 offset:13696
	ds_read_u16 v252, v49 offset:4672
	ds_read_u16 v253, v49 offset:4816
	ds_read_u16 v254, v49 offset:4960
	ds_read_u16 v255, v49 offset:5104
	s_waitcnt lgkmcnt(0)
	v_pk_mul_f32 v[4:5], v[4:5], v[20:21]
	v_pk_mul_f32 v[6:7], v[6:7], v[22:23]
	v_lshlrev_b32_e32 v252, 16, v252
	v_lshlrev_b32_e32 v253, 16, v253
	v_lshlrev_b32_e32 v254, 16, v254
	v_lshlrev_b32_e32 v255, 16, v255
	v_pk_mul_f32 v[252:253], v[206:207], v[252:253] op_sel_hi:[0,1]
	v_pk_mul_f32 v[254:255], v[206:207], v[254:255] op_sel_hi:[0,1]
	v_cvt_pk_bf16_f32 v252, v252, v253
	v_cvt_pk_bf16_f32 v253, v254, v255
	s_nop 1
	v_mfma_f32_16x16x16_bf16 v[4:7], v[252:253], v[16:17], v[4:7]
	ds_read_b128 v[20:23], v143 offset:13760
	ds_read_b32 v206, v144 offset:13760
	ds_read_u16 v252, v49 offset:4704
	ds_read_u16 v253, v49 offset:4848
	ds_read_u16 v254, v49 offset:4992
	ds_read_u16 v255, v49 offset:5136
	s_waitcnt lgkmcnt(0)
	v_pk_mul_f32 v[0:1], v[0:1], v[20:21]
	v_pk_mul_f32 v[2:3], v[2:3], v[22:23]
	v_lshlrev_b32_e32 v252, 16, v252
	v_lshlrev_b32_e32 v253, 16, v253
	v_lshlrev_b32_e32 v254, 16, v254
	v_lshlrev_b32_e32 v255, 16, v255
	v_pk_mul_f32 v[252:253], v[206:207], v[252:253] op_sel_hi:[0,1]
	v_pk_mul_f32 v[254:255], v[206:207], v[254:255] op_sel_hi:[0,1]
	v_cvt_pk_bf16_f32 v252, v252, v253
	v_cvt_pk_bf16_f32 v253, v254, v255
	s_nop 1
	v_mfma_f32_16x16x16_bf16 v[0:3], v[252:253], v[16:17], v[0:3]
.Lkt0_end:
.LBB0_584:
	s_cmp_lt_u32 s2, 14
	s_cbranch_scc1 .Lx584_w
	s_waitcnt vmcnt(0)

.LBB0_604:
	v_cndmask_b32_e64 v16, 0, v32, s[24:25]
	v_cndmask_b32_e64 v17, 0, v33, s[30:31]
	v_cndmask_b32_e64 v18, 0, v34, s[34:35]
	v_cndmask_b32_e64 v19, 0, v35, s[36:37]
	v_cvt_pk_bf16_f32 v28, v16, v17
	v_cvt_pk_bf16_f32 v29, v18, v19
	v_cndmask_b32_e64 v20, 0, v36, s[22:23]
	v_cndmask_b32_e64 v21, v37, 0, s[24:25]
	v_cndmask_b32_e64 v22, 0, v38, s[26:27]
	v_cndmask_b32_e64 v23, 0, v39, s[28:29]
	v_cvt_pk_bf16_f32 v16, v24, v25
	v_cvt_pk_bf16_f32 v17, v26, v27
	s_and_b64 vcc, exec, s[40:41]
	s_nop 0
	v_mfma_f32_16x16x16_bf16 v[16:19], v[28:29], v[16:17], v[24:27]
	s_nop 2
	v_cvt_pk_bf16_f32 v24, v20, v21
	v_cvt_pk_bf16_f32 v25, v22, v23
	s_nop 1
	v_mfma_f32_16x16x16_bf16 v[20:23], v[28:29], v[24:25], 0
	v_mfma_f32_16x16x16_bf16 v[24:27], v[24:25], v[28:29], 0
	s_nop 7
	v_cvt_pk_bf16_f32 v24, v24, v25
	v_cvt_pk_bf16_f32 v25, v26, v27
	v_cvt_pk_bf16_f32 v26, v16, v17
	v_cvt_pk_bf16_f32 v27, v18, v19
	s_nop 1
	v_mfma_f32_16x16x16_bf16 v[16:19], v[24:25], v[26:27], v[16:19]
	v_cvt_pk_bf16_f32 v26, v20, v21
	v_cvt_pk_bf16_f32 v27, v22, v23
	s_nop 1
	v_mfma_f32_16x16x16_bf16 v[20:23], v[24:25], v[26:27], 0
	v_mfma_f32_16x16x16_bf16 v[24:27], v[26:27], v[24:25], 0
	s_nop 6
	v_cvt_pk_bf16_f32 v20, v20, v21
	v_cvt_pk_bf16_f32 v21, v22, v23
	v_cvt_pk_bf16_f32 v24, v24, v25
	v_cvt_pk_bf16_f32 v25, v26, v27
	v_cvt_pk_bf16_f32 v26, v16, v17
	v_cvt_pk_bf16_f32 v27, v18, v19
	v_mfma_f32_16x16x16_bf16 v[20:23], v[20:21], v[24:25], 0
	s_nop 0
	v_mfma_f32_16x16x16_bf16 v[16:19], v[24:25], v[26:27], v[16:19]
	s_nop 5
	v_cvt_pk_bf16_f32 v20, v20, v21
	v_cvt_pk_bf16_f32 v21, v22, v23
	v_cvt_pk_bf16_f32 v22, v16, v17
	v_cvt_pk_bf16_f32 v23, v18, v19
	s_nop 1
	v_mfma_f32_16x16x16_bf16 v[16:19], v[20:21], v[22:23], v[16:19]
	s_nop 7
	v_cvt_pk_bf16_f32 v16, v16, v17
	v_cvt_pk_bf16_f32 v17, v18, v19
	ds_read_b128 v[20:23], v143 offset:13568
	ds_read_b32 v206, v144 offset:13568
	ds_read_u16 v252, v49 offset:4608
	ds_read_u16 v253, v49 offset:4752
	ds_read_u16 v254, v49 offset:4896
	ds_read_u16 v255, v49 offset:5040
	s_and_b64 vcc, exec, s[40:41]
	s_cbranch_vccnz .Lkt1_nov
	ds_read_u16 v18, v49 offset:6912
	ds_read_u16 v19, v49 offset:7056
	ds_read_u16 v205, v49 offset:7200
	ds_read_u16 v251, v49 offset:7344
	s_waitcnt lgkmcnt(0)
	v_pk_mul_f32 v[12:13], v[12:13], v[20:21]
	v_pk_mul_f32 v[14:15], v[14:15], v[22:23]
	v_lshlrev_b32_e32 v252, 16, v252
	v_lshlrev_b32_e32 v253, 16, v253
	v_lshlrev_b32_e32 v254, 16, v254
	v_lshlrev_b32_e32 v255, 16, v255
	v_pk_mul_f32 v[252:253], v[206:207], v[252:253] op_sel_hi:[0,1]
	v_pk_mul_f32 v[254:255], v[206:207], v[254:255] op_sel_hi:[0,1]
	v_cvt_pk_bf16_f32 v252, v252, v253
	v_cvt_pk_bf16_f32 v253, v254, v255
	v_lshlrev_b32_e32 v18, 16, v18
	v_lshlrev_b32_e32 v19, 16, v19
	v_mfma_f32_16x16x16_bf16 v[12:15], v[252:253], v[16:17], v[12:15]
	v_lshlrev_b32_e32 v205, 16, v205
	v_lshlrev_b32_e32 v251, 16, v251
	v_pk_mul_f32 v[18:19], v[206:207], v[18:19] op_sel_hi:[0,1]
	v_mul_f32_e32 v205, v206, v205
	v_mul_f32_e32 v251, v206, v251
	v_cvt_pk_bf16_f32 v18, v18, v19
	v_cvt_pk_bf16_f32 v19, v205, v251
	s_nop 1
	v_mfma_f32_16x16x16_bf16 v[12:15], v[18:19], v[98:99], v[12:15]
	ds_read_b128 v[20:23], v143 offset:13632
	ds_read_b32 v206, v144 offset:13632
	ds_read_u16 v252, v49 offset:4640
	ds_read_u16 v253, v49 offset:4784
	ds_read_u16 v254, v49 offset:4928
	ds_read_u16 v255, v49 offset:5072
	ds_read_u16 v18, v49 offset:6944
	ds_read_u16 v19, v49 offset:7088
	ds_read_u16 v205, v49 offset:7232
	ds_read_u16 v251, v49 offset:7376
	s_waitcnt lgkmcnt(0)
	v_pk_mul_f32 v[8:9], v[8:9], v[20:21]
	v_pk_mul_f32 v[10:11], v[10:11], v[22:23]
	v_lshlrev_b32_e32 v252, 16, v252
	v_lshlrev_b32_e32 v253, 16, v253
	v_lshlrev_b32_e32 v254, 16, v254
	v_lshlrev_b32_e32 v255, 16, v255
	v_pk_mul_f32 v[252:253], v[206:207], v[252:253] op_sel_hi:[0,1]
	v_pk_mul_f32 v[254:255], v[206:207], v[254:255] op_sel_hi:[0,1]
	v_cvt_pk_bf16_f32 v252, v252, v253
	v_cvt_pk_bf16_f32 v253, v254, v255
	v_lshlrev_b32_e32 v18, 16, v18
	v_lshlrev_b32_e32 v19, 16, v19
	v_mfma_f32_16x16x16_bf16 v[8:11], v[252:253], v[16:17], v[8:11]
	v_lshlrev_b32_e32 v205, 16, v205
	v_lshlrev_b32_e32 v251, 16, v251
	v_pk_mul_f32 v[18:19], v[206:207], v[18:19] op_sel_hi:[0,1]
	v_mul_f32_e32 v205, v206, v205
	v_mul_f32_e32 v251, v206, v251
	v_cvt_pk_bf16_f32 v18, v18, v19
	v_cvt_pk_bf16_f32 v19, v205, v251
	s_nop 1
	v_mfma_f32_16x16x16_bf16 v[8:11], v[18:19], v[98:99], v[8:11]
	ds_read_b128 v[20:23], v143 offset:13696
	ds_read_b32 v206, v144 offset:13696
	ds_read_u16 v252, v49 offset:4672
	ds_read_u16 v253, v49 offset:4816
	ds_read_u16 v254, v49 offset:4960
	ds_read_u16 v255, v49 offset:5104
	ds_read_u16 v18, v49 offset:6976
	ds_read_u16 v19, v49 offset:7120
	ds_read_u16 v205, v49 offset:7264
	ds_read_u16 v251, v49 offset:7408
	s_waitcnt lgkmcnt(0)
	v_pk_mul_f32 v[4:5], v[4:5], v[20:21]
	v_pk_mul_f32 v[6:7], v[6:7], v[22:23]
	v_lshlrev_b32_e32 v252, 16, v252
	v_lshlrev_b32_e32 v253, 16, v253
	v_lshlrev_b32_e32 v254, 16, v254
	v_lshlrev_b32_e32 v255, 16, v255
	v_pk_mul_f32 v[252:253], v[206:207], v[252:253] op_sel_hi:[0,1]
	v_pk_mul_f32 v[254:255], v[206:207], v[254:255] op_sel_hi:[0,1]
	v_cvt_pk_bf16_f32 v252, v252, v253
	v_cvt_pk_bf16_f32 v253, v254, v255
	v_lshlrev_b32_e32 v18, 16, v18
	v_lshlrev_b32_e32 v19, 16, v19
	v_mfma_f32_16x16x16_bf16 v[4:7], v[252:253], v[16:17], v[4:7]
	v_lshlrev_b32_e32 v205, 16, v205
	v_lshlrev_b32_e32 v251, 16, v251
	v_pk_mul_f32 v[18:19], v[206:207], v[18:19] op_sel_hi:[0,1]
	v_mul_f32_e32 v205, v206, v205
	v_mul_f32_e32 v251, v206, v251
	v_cvt_pk_bf16_f32 v18, v18, v19
	v_cvt_pk_bf16_f32 v19, v205, v251
	s_nop 1
	v_mfma_f32_16x16x16_bf16 v[4:7], v[18:19], v[98:99], v[4:7]
	ds_read_b128 v[20:23], v143 offset:13760
	ds_read_b32 v206, v144 offset:13760
	ds_read_u16 v252, v49 offset:4704
	ds_read_u16 v253, v49 offset:4848
	ds_read_u16 v254, v49 offset:4992
	ds_read_u16 v255, v49 offset:5136
	ds_read_u16 v18, v49 offset:7008
	ds_read_u16 v19, v49 offset:7152
	ds_read_u16 v205, v49 offset:7296
	ds_read_u16 v251, v49 offset:7440
	s_waitcnt lgkmcnt(0)
	v_pk_mul_f32 v[0:1], v[0:1], v[20:21]
	v_pk_mul_f32 v[2:3], v[2:3], v[22:23]
	v_lshlrev_b32_e32 v252, 16, v252
	v_lshlrev_b32_e32 v253, 16, v253
	v_lshlrev_b32_e32 v254, 16, v254
	v_lshlrev_b32_e32 v255, 16, v255
	v_pk_mul_f32 v[252:253], v[206:207], v[252:253] op_sel_hi:[0,1]
	v_pk_mul_f32 v[254:255], v[206:207], v[254:255] op_sel_hi:[0,1]
	v_cvt_pk_bf16_f32 v252, v252, v253
	v_cvt_pk_bf16_f32 v253, v254, v255
	v_lshlrev_b32_e32 v18, 16, v18
	v_lshlrev_b32_e32 v19, 16, v19
	v_mfma_f32_16x16x16_bf16 v[0:3], v[252:253], v[16:17], v[0:3]
	v_lshlrev_b32_e32 v205, 16, v205
	v_lshlrev_b32_e32 v251, 16, v251
	v_pk_mul_f32 v[18:19], v[206:207], v[18:19] op_sel_hi:[0,1]
	v_mul_f32_e32 v205, v206, v205
	v_mul_f32_e32 v251, v206, v251
	v_cvt_pk_bf16_f32 v18, v18, v19
	v_cvt_pk_bf16_f32 v19, v205, v251
	s_nop 1
	v_mfma_f32_16x16x16_bf16 v[0:3], v[18:19], v[98:99], v[0:3]
	s_branch .Lkt1_end
.Lkt1_nov:
	s_waitcnt lgkmcnt(0)
	v_pk_mul_f32 v[12:13], v[12:13], v[20:21]
	v_pk_mul_f32 v[14:15], v[14:15], v[22:23]
	v_lshlrev_b32_e32 v252, 16, v252
	v_lshlrev_b32_e32 v253, 16, v253
	v_lshlrev_b32_e32 v254, 16, v254
	v_lshlrev_b32_e32 v255, 16, v255
	v_pk_mul_f32 v[252:253], v[206:207], v[252:253] op_sel_hi:[0,1]
	v_pk_mul_f32 v[254:255], v[206:207], v[254:255] op_sel_hi:[0,1]
	v_cvt_pk_bf16_f32 v252, v252, v253
	v_cvt_pk_bf16_f32 v253, v254, v255
	s_nop 1
	v_mfma_f32_16x16x16_bf16 v[12:15], v[252:253], v[16:17], v[12:15]
	ds_read_b128 v[20:23], v143 offset:13632
	ds_read_b32 v206, v144 offset:13632
	ds_read_u16 v252, v49 offset:4640
	ds_read_u16 v253, v49 offset:4784
	ds_read_u16 v254, v49 offset:4928
	ds_read_u16 v255, v49 offset:5072
	s_waitcnt lgkmcnt(0)
	v_pk_mul_f32 v[8:9], v[8:9], v[20:21]
	v_pk_mul_f32 v[10:11], v[10:11], v[22:23]
	v_lshlrev_b32_e32 v252, 16, v252
	v_lshlrev_b32_e32 v253, 16, v253
	v_lshlrev_b32_e32 v254, 16, v254
	v_lshlrev_b32_e32 v255, 16, v255
	v_pk_mul_f32 v[252:253], v[206:207], v[252:253] op_sel_hi:[0,1]
	v_pk_mul_f32 v[254:255], v[206:207], v[254:255] op_sel_hi:[0,1]
	v_cvt_pk_bf16_f32 v252, v252, v253
	v_cvt_pk_bf16_f32 v253, v254, v255
	s_nop 1
	v_mfma_f32_16x16x16_bf16 v[8:11], v[252:253], v[16:17], v[8:11]
	ds_read_b128 v[20:23], v143 offset:13696
	ds_read_b32 v206, v144 offset:13696
	ds_read_u16 v252, v49 offset:4672
	ds_read_u16 v253, v49 offset:4816
	ds_read_u16 v254, v49 offset:4960
	ds_read_u16 v255, v49 offset:5104
	s_waitcnt lgkmcnt(0)
	v_pk_mul_f32 v[4:5], v[4:5], v[20:21]
	v_pk_mul_f32 v[6:7], v[6:7], v[22:23]
	v_lshlrev_b32_e32 v252, 16, v252
	v_lshlrev_b32_e32 v253, 16, v253
	v_lshlrev_b32_e32 v254, 16, v254
	v_lshlrev_b32_e32 v255, 16, v255
	v_pk_mul_f32 v[252:253], v[206:207], v[252:253] op_sel_hi:[0,1]
	v_pk_mul_f32 v[254:255], v[206:207], v[254:255] op_sel_hi:[0,1]
	v_cvt_pk_bf16_f32 v252, v252, v253
	v_cvt_pk_bf16_f32 v253, v254, v255
	s_nop 1
	v_mfma_f32_16x16x16_bf16 v[4:7], v[252:253], v[16:17], v[4:7]
	ds_read_b128 v[20:23], v143 offset:13760
	ds_read_b32 v206, v144 offset:13760
	ds_read_u16 v252, v49 offset:4704
	ds_read_u16 v253, v49 offset:4848
	ds_read_u16 v254, v49 offset:4992
	ds_read_u16 v255, v49 offset:5136
	s_waitcnt lgkmcnt(0)
	v_pk_mul_f32 v[0:1], v[0:1], v[20:21]
	v_pk_mul_f32 v[2:3], v[2:3], v[22:23]
	v_lshlrev_b32_e32 v252, 16, v252
	v_lshlrev_b32_e32 v253, 16, v253
	v_lshlrev_b32_e32 v254, 16, v254
	v_lshlrev_b32_e32 v255, 16, v255
	v_pk_mul_f32 v[252:253], v[206:207], v[252:253] op_sel_hi:[0,1]
	v_pk_mul_f32 v[254:255], v[206:207], v[254:255] op_sel_hi:[0,1]
	v_cvt_pk_bf16_f32 v252, v252, v253
	v_cvt_pk_bf16_f32 v253, v254, v255
	s_nop 1
	v_mfma_f32_16x16x16_bf16 v[0:3], v[252:253], v[16:17], v[0:3]
.Lkt1_end:
.LBB0_612:
	s_andn2_b64 vcc, exec, s[46:47]
	s_mov_b64 s[0:1], -1
	s_cbranch_vccnz .LBB0_555
